# v82 candidate: v81 + redundant QK s_nop removed + SwiGLU log2e fold (96 v_mul removed, f32 throughout)
# speedup vs baseline: 1.0008x; 1.0008x over previous
; #define SBAR() __builtin_amdgcn_sched_barrier(0)
; #define MM16(A_, B_, C_) __builtin_amdgcn_mfma_f32_16x16x32_bf16(A_, B_, C_, 0, 0, 0)
; __device__ __forceinline__ void qkt2(f32x4a (&s)[4][2], const char* Ks, int ko0, int ko1, const bf16x8 (&qr)[2][2]) {
;   const f32x4a z4 = {0.f, 0.f, 0.f, 0.f};
; #pragma unroll
;   for (int h2 = 0; h2 < 2; ++h2) { bf16x8 kf[2][2];
; #pragma unroll
;     for (int k2 = 0; k2 < 2; ++k2) { kf[k2][0] = *reinterpret_cast<const bf16x8*>(Ks + ko0 + 2048 * (2 * h2 + k2)); kf[k2][1] = *reinterpret_cast<const bf16x8*>(Ks + ko1 + 2048 * (2 * h2 + k2)); }
;     SBAR();
; #pragma unroll
;     for (int k2 = 0; k2 < 2; ++k2)
; #pragma unroll
;       for (int qb = 0; qb < 2; ++qb) s[2 * h2 + k2][qb] = MM16(kf[k2][0], qr[qb][0], z4);
; #pragma unroll
;     for (int k2 = 0; k2 < 2; ++k2)
; #pragma unroll
;       for (int qb = 0; qb < 2; ++qb) s[2 * h2 + k2][qb] = MM16(kf[k2][1], qr[qb][1], s[2 * h2 + k2][qb]);
;     SBAR(); }
; }
; __device__ __forceinline__ void finishSM(f32x4a (&s)[4][2], float& l0, float& l1, bf16x8 (&pa)[2][2]) {
;     ...
;   float a0 = 0.f, a1 = 0.f, a2 = 0.f, a3 = 0.f, b0 = 0.f, b1 = 0.f, b2 = 0.f, b3 = 0.f;
; #pragma unroll
;   for (int kb = 0; kb < 4; ++kb) { a0 += s[kb][0][0]; a1 += s[kb][0][1]; a2 += s[kb][0][2]; a3 += s[kb][0][3]; b0 += s[kb][1][0]; b1 += s[kb][1][1]; b2 += s[kb][1][2]; b3 += s[kb][1][3]; }
;   l0 += (a0 + a1) + (a2 + a3); l1 += (b0 + b1) + (b2 + b3);
.Lattn_xgo:
	s_cmpk_eq_i32 s44, 0xff
	s_cbranch_scc1 .LBB0_575
	s_waitcnt lgkmcnt(0)
	v_mfma_f32_16x16x32_bf16 v[80:83], v[56:59], v[4:7], 0
	v_add_f32_e32 v188, v188, v194
	v_add_f32_e32 v189, v189, v195
	v_mfma_f32_16x16x32_bf16 v[88:91], v[56:59], v[12:15], 0
	v_add_f32_e32 v184, v184, v192
	v_add_f32_e32 v185, v185, v193
	v_mfma_f32_16x16x32_bf16 v[92:95], v[60:63], v[4:7], 0
	v_add_f32_e32 v174, v174, v190
	v_add_f32_e32 v175, v175, v191
	v_mfma_f32_16x16x32_bf16 v[96:99], v[60:63], v[12:15], 0
	v_add_f32_e32 v170, v170, v186
	v_add_f32_e32 v171, v171, v187
	v_mfma_f32_16x16x32_bf16 v[56:59], v[64:67], v[8:11], v[80:83]
	v_add_f32_e32 v172, v172, v188
	v_add_f32_e32 v173, v173, v189
	v_mfma_f32_16x16x32_bf16 v[60:63], v[64:67], v[16:19], v[88:91]
	v_add_f32_e32 v168, v168, v184
	v_add_f32_e32 v169, v169, v185
	v_mfma_f32_16x16x32_bf16 v[64:67], v[68:71], v[8:11], v[92:95]
	v_add_f32_e32 v166, v166, v174
	v_add_f32_e32 v167, v167, v175
	v_mfma_f32_16x16x32_bf16 v[68:71], v[68:71], v[16:19], v[96:99]
	v_add_f32_e32 v162, v162, v170
	v_add_f32_e32 v163, v163, v171
	ds_read_b128 v[80:83], v178 offset:4096
	ds_read_b128 v[88:91], v178 offset:6144
	ds_read_b128 v[92:95], v179 offset:4096
	ds_read_b128 v[96:99], v179 offset:6144
	s_waitcnt lgkmcnt(3)
	v_mfma_f32_16x16x32_bf16 v[240:243], v[80:83], v[4:7], 0
	v_add_f32_e32 v164, v164, v172
	v_add_f32_e32 v165, v165, v173
	v_mfma_f32_16x16x32_bf16 v[244:247], v[80:83], v[12:15], 0
	v_add_f32_e32 v160, v160, v168
	v_add_f32_e32 v161, v161, v169
	s_waitcnt lgkmcnt(2)
	v_mfma_f32_16x16x32_bf16 v[248:251], v[88:91], v[4:7], 0
	v_add_f32_e32 v158, v158, v166
	v_add_f32_e32 v159, v159, v167
	v_mfma_f32_16x16x32_bf16 v[228:231], v[88:91], v[12:15], 0
	v_add_f32_e32 v156, v156, v162
	v_add_f32_e32 v157, v157, v163
	s_waitcnt lgkmcnt(1)
	v_mfma_f32_16x16x32_bf16 v[80:83], v[92:95], v[8:11], v[240:243]
	v_add_f32_e32 v160, v164, v160
	v_add_f32_e32 v161, v165, v161
	v_mfma_f32_16x16x32_bf16 v[88:91], v[92:95], v[16:19], v[244:247]
	v_add_f32_e32 v156, v158, v156
	v_add_f32_e32 v157, v159, v157
	s_waitcnt lgkmcnt(0)
	v_mfma_f32_16x16x32_bf16 v[92:95], v[96:99], v[8:11], v[248:251]
	v_add_f32_e32 v156, v160, v156
	v_add_f32_e32 v157, v161, v157
	v_mfma_f32_16x16x32_bf16 v[96:99], v[96:99], v[16:19], v[228:231]
	v_add_f32_e32 v154, v154, v156
	v_add_f32_e32 v155, v155, v157
	s_branch .LBB0_576
